# hgrn state chain: 16 log-decay loads per step use one base + immediate offsets (56 fewer address instructions per step)
# speedup vs baseline: 1.0086x; 1.0020x over previous
.LBB0_663:
	s_add_i32 s59, s58, 1
	s_cmp_lt_u32 s58, 3
	s_cselect_b32 s16, 3, 39
	s_add_i32 s26, s16, s34
	s_and_b64 s[16:17], s[14:15], exec
	s_cselect_b32 s16, s59, s26
	s_lshl_b32 s16, s16, 6
	v_add_u32_e32 v48, s16, v120
	v_ashrrev_i32_e32 v49, 31, v48
	v_lshlrev_b64 v[50:51], 10, v[48:49]
	v_lshl_add_u64 v[50:51], v[84:85], 0, v[50:51]
	s_mov_b64 s[98:99], 0x1000
	s_waitcnt vmcnt(19)
	v_cvt_f32_f16_e32 v142, v111
	global_load_ushort v111, v[50:51], off
	s_waitcnt vmcnt(19)
	v_cvt_f32_f16_e32 v143, v113
	global_load_ushort v113, v[50:51], off offset:1024
	s_waitcnt vmcnt(19)
	v_cvt_f32_f16_e32 v140, v114
	global_load_ushort v114, v[50:51], off offset:2048
	s_waitcnt vmcnt(19)
	v_cvt_f32_f16_e32 v141, v115
	global_load_ushort v115, v[50:51], off offset:3072
	v_lshl_add_u64 v[50:51], v[50:51], 0, s[98:99]
	s_waitcnt vmcnt(19)
	v_cvt_f32_f16_e32 v138, v116
	global_load_ushort v116, v[50:51], off
	s_waitcnt vmcnt(19)
	v_cvt_f32_f16_e32 v139, v117
	global_load_ushort v117, v[50:51], off offset:1024
	s_waitcnt vmcnt(19)
	v_cvt_f32_f16_e32 v136, v118
	global_load_ushort v118, v[50:51], off offset:2048
	s_waitcnt vmcnt(19)
	v_cvt_f32_f16_e32 v137, v119
	global_load_ushort v119, v[50:51], off offset:3072
	v_lshl_add_u64 v[50:51], v[50:51], 0, s[98:99]
	s_waitcnt vmcnt(19)
	v_cvt_f32_f16_e32 v134, v121
	global_load_ushort v121, v[50:51], off
	s_waitcnt vmcnt(19)
	v_cvt_f32_f16_e32 v135, v122
	global_load_ushort v122, v[50:51], off offset:1024
	s_waitcnt vmcnt(19)
	v_cvt_f32_f16_e32 v132, v123
	global_load_ushort v123, v[50:51], off offset:2048
	s_waitcnt vmcnt(19)
	v_cvt_f32_f16_e32 v133, v124
	global_load_ushort v124, v[50:51], off offset:3072
	v_lshl_add_u64 v[50:51], v[50:51], 0, s[98:99]
	s_waitcnt vmcnt(19)
	v_cvt_f32_f16_e32 v130, v125
	global_load_ushort v125, v[50:51], off
	s_waitcnt vmcnt(19)
	v_cvt_f32_f16_e32 v131, v126
	global_load_ushort v126, v[50:51], off offset:1024
	s_ashr_i32 s17, s16, 31
	s_waitcnt vmcnt(19)
	v_cvt_f32_f16_e32 v88, v127
	s_waitcnt vmcnt(18)
	v_cvt_f32_f16_e32 v129, v128
	global_load_ushort v127, v[50:51], off offset:2048
	global_load_ushort v128, v[50:51], off offset:3072
	v_lshl_add_u64 v[48:49], s[16:17], 1, v[86:87]
	global_load_dwordx4 v[60:63], v[48:49], off
	global_load_dwordx4 v[56:59], v[48:49], off offset:32
	global_load_dwordx4 v[52:55], v[48:49], off offset:64
	s_nop 0
	global_load_dwordx4 v[48:51], v[48:49], off offset:96
	v_cndmask_b32_e64 v89, 0, 1, s[18:19]
	s_mov_b64 s[56:57], -1
	v_cmp_ne_u32_e64 s[16:17], 1, v89
	s_andn2_b64 vcc, exec, s[18:19]
	s_cbranch_vccnz .LBB0_665
	v_add_f32_e32 v89, 0, v129
	v_add_f32_e32 v146, v89, v88
	v_add_f32_e32 v148, v146, v131
	v_add_f32_e32 v150, v148, v130
	v_add_f32_e32 v152, v150, v133
	v_add_f32_e32 v153, v152, v132
	v_add_f32_e32 v154, v153, v135
	v_add_f32_e32 v156, v154, v134
	v_add_f32_e32 v157, v156, v137
	v_add_f32_e32 v158, v157, v136
	v_add_f32_e32 v159, v158, v139
	v_add_f32_e32 v160, v159, v138
	v_add_f32_e32 v161, v160, v141
	v_add_f32_e32 v162, v161, v140
	v_add_f32_e32 v163, v162, v143
	v_add_f32_e32 v165, v163, v142
	s_mov_b64 s[56:57], 0

	.amdhsa_kernel _Z6mk_fwd4Args
		.amdhsa_group_segment_fixed_size 0
		.amdhsa_private_segment_fixed_size 0
		.amdhsa_kernarg_size 448
		.amdhsa_user_sgpr_count 2
		.amdhsa_user_sgpr_dispatch_ptr 0
		.amdhsa_user_sgpr_queue_ptr 0
		.amdhsa_user_sgpr_kernarg_segment_ptr 1
		.amdhsa_user_sgpr_dispatch_id 0
		.amdhsa_user_sgpr_kernarg_preload_length 0
		.amdhsa_user_sgpr_kernarg_preload_offset 0
		.amdhsa_user_sgpr_private_segment_size 0
		.amdhsa_uses_dynamic_stack 0
		.amdhsa_enable_private_segment 0
		.amdhsa_system_sgpr_workgroup_id_x 1
		.amdhsa_system_sgpr_workgroup_id_y 0
		.amdhsa_system_sgpr_workgroup_id_z 0
		.amdhsa_system_sgpr_workgroup_info 0
		.amdhsa_system_vgpr_workitem_id 0
		.amdhsa_next_free_vgpr 256
		.amdhsa_next_free_sgpr 102
		.amdhsa_accum_offset 256
		.amdhsa_reserve_vcc 1
		.amdhsa_float_round_mode_32 0
		.amdhsa_float_round_mode_16_64 0
		.amdhsa_float_denorm_mode_32 3
		.amdhsa_float_denorm_mode_16_64 3
		.amdhsa_dx10_clamp 1
		.amdhsa_ieee_mode 1
		.amdhsa_fp16_overflow 0
		.amdhsa_tg_split 0
		.amdhsa_exception_fp_ieee_invalid_op 0
		.amdhsa_exception_fp_denorm_src 0
		.amdhsa_exception_fp_ieee_div_zero 0
		.amdhsa_exception_fp_ieee_overflow 0
		.amdhsa_exception_fp_ieee_underflow 0
		.amdhsa_exception_fp_ieee_inexact 0
		.amdhsa_exception_int_div_zero 0
	.end_amdhsa_kernel

amdhsa.kernels:
  - .agpr_count:     0
    .args:
      - .offset:         0
        .size:           192
        .value_kind:     by_value
      - .offset:         192
        .size:           4
        .value_kind:     hidden_block_count_x
      - .offset:         196
        .size:           4
        .value_kind:     hidden_block_count_y
      - .offset:         200
        .size:           4
        .value_kind:     hidden_block_count_z
      - .offset:         204
        .size:           2
        .value_kind:     hidden_group_size_x
      - .offset:         206
        .size:           2
        .value_kind:     hidden_group_size_y
      - .offset:         208
        .size:           2
        .value_kind:     hidden_group_size_z
      - .offset:         210
        .size:           2
        .value_kind:     hidden_remainder_x
      - .offset:         212
        .size:           2
        .value_kind:     hidden_remainder_y
      - .offset:         214
        .size:           2
        .value_kind:     hidden_remainder_z
      - .offset:         232
        .size:           8
        .value_kind:     hidden_global_offset_x
      - .offset:         240
        .size:           8
        .value_kind:     hidden_global_offset_y
      - .offset:         248
        .size:           8
        .value_kind:     hidden_global_offset_z
      - .offset:         256
        .size:           2
        .value_kind:     hidden_grid_dims
      - .offset:         312
        .size:           4
        .value_kind:     hidden_dynamic_lds_size
    .group_segment_fixed_size: 0
    .kernarg_segment_align: 8
    .kernarg_segment_size: 448
    .language:       OpenCL C
    .language_version:
      - 2
      - 0
    .max_flat_workgroup_size: 512
    .name:           _Z6mk_fwd4Args
    .private_segment_fixed_size: 0
    .sgpr_count:     108
    .sgpr_spill_count: 9
    .symbol:         _Z6mk_fwd4Args.kd
    .uniform_work_group_size: 1
    .uses_dynamic_stack: false
    .vgpr_count:     256
    .vgpr_spill_count: 0
    .wavefront_size: 64
